# weight conversion rebalanced: FFN f down weights converted in GU phase f tail (phase 13 idle tail used), FFN0-down loop merged, rotated worker ids, pos-bias dot loop unrolled
# speedup vs baseline: 1.0156x; 1.0053x over previous
.LBB0_819:
	v_readlane_b32 s16, v254, 42
	s_cmp_lg_u32 s16, 4
	v_readlane_b32 s8, v253, 18
	s_cselect_b64 s[6:7], -1, 0
	v_readlane_b32 s9, v253, 19
	s_and_b64 s[6:7], s[8:9], s[6:7]
	s_cmpk_gt_i32 s60, 0x7f
	s_mov_b32 s0, s60
	s_cselect_b64 s[8:9], -1, 0
	v_writelane_b32 v254, s0, 34
	s_and_b64 s[6:7], s[6:7], s[8:9]
	s_andn2_b64 vcc, exec, s[6:7]
	v_writelane_b32 v254, s1, 35
	s_cbranch_vccnz .LBB0_984
	v_readlane_b32 s7, v254, 36
	s_mul_i32 s0, s7, 0x4100
	v_readlane_b32 s8, v254, 34
	s_add_i32 s6, s0, 0
	s_lshl_b32 s0, s8, 3
	s_add_i32 s0, s0, s7
	s_add_i32 s8, s0, 0xfffffc00
	s_cmp_lg_u32 s16, 0
	v_readlane_b32 s9, v254, 35
	s_cbranch_scc1 .LBB0_945
.LBB0_860:
	s_cmpk_gt_i32 s8, 0x4bf
	s_cbranch_scc1 .LBB0_939
	v_lshlrev_b32_e32 v0, 2, v210
	v_and_b32_e32 v68, 60, v0
	v_lshlrev_b32_e32 v0, 3, v210
	v_and_b32_e32 v0, 56, v0
	s_waitcnt lgkmcnt(0)
	v_mul_u32_u24_e32 v3, 0x104, v0
	v_lshlrev_b32_e32 v0, 1, v0
	v_lshrrev_b32_e32 v86, 3, v210
	v_lshl_add_u64 v[4:5], s[4:5], 0, v[0:1]
	s_mov_b64 s[10:11], 0x4b80000
	v_lshrrev_b32_e32 v66, 4, v210
	v_lshl_add_u64 v[70:71], v[4:5], 0, s[10:11]
	v_lshlrev_b32_e32 v0, 2, v86
	s_mov_b64 s[10:11], 0x4b00000
	v_lshlrev_b32_e32 v2, 2, v68
	s_movk_i32 s0, 0x104
	v_add3_u32 v87, s6, v3, v0
	v_lshl_add_u64 v[72:73], v[4:5], 0, s[10:11]
	s_mov_b64 s[10:11], 0x4900000
	v_or_b32_e32 v0, 4, v66
	v_readlane_b32 s36, v253, 1
	v_add_u32_e32 v6, s6, v2
	v_lshl_add_u64 v[74:75], v[4:5], 0, s[10:11]
	v_mul_u32_u24_e32 v7, 0x104, v0
	v_mad_u32_u24 v8, v0, s0, v205
	v_mad_u32_u24 v9, v0, s0, v206
	v_mad_u32_u24 v0, v0, s0, v207
	s_mov_b64 s[10:11], 0x4300000
	v_mov_b32_e32 v3, v1
	v_readlane_b32 s48, v253, 13
	v_readlane_b32 s49, v253, 14
	v_mad_u32_u24 v69, v66, s0, v6
	v_or_b32_e32 v88, 8, v86
	v_or_b32_e32 v89, 16, v86
	v_or_b32_e32 v90, 24, v86
	v_or_b32_e32 v91, 32, v86
	v_or_b32_e32 v92, 40, v86
	v_or_b32_e32 v93, 48, v86
	v_or_b32_e32 v94, 56, v86
	v_lshl_add_u64 v[76:77], v[4:5], 0, s[10:11]
	v_lshl_add_u64 v[78:79], s[48:49], 0, v[2:3]
	v_lshl_add_u64 v[80:81], s[82:83], 0, v[2:3]
	v_mov_b32_e32 v67, v1
	s_add_i32 s92, s8, 0x300
	s_and_b32 s92, s92, 0x3ff
	s_lshl_b32 s7, s92, 6
	s_lshl_b32 s9, s92, 5
	s_lshl_b32 s16, s92, 4
	s_lshl_b32 s17, s92, 2
	v_add_u32_e32 v95, v6, v7
	v_add_u32_e32 v96, v6, v9
	v_add_u32_e32 v97, v6, v8
	v_add_u32_e32 v98, v6, v0
	s_mov_b32 s18, s92
	v_readlane_b32 s37, v253, 2
	v_readlane_b32 s38, v253, 3
	v_readlane_b32 s39, v253, 4
	v_readlane_b32 s40, v253, 5
	v_readlane_b32 s41, v253, 6
	v_readlane_b32 s42, v253, 7
	v_readlane_b32 s43, v253, 8
	v_readlane_b32 s44, v253, 9
	v_readlane_b32 s45, v253, 10
	v_readlane_b32 s46, v253, 11
	v_readlane_b32 s47, v253, 12
	v_readlane_b32 s50, v253, 15
	v_readlane_b32 s51, v253, 16
	s_branch .LBB0_865

.LBB0_941:
	global_load_dword v106, v[2:3], off
	global_load_dword v139, v[4:5], off
	v_lshl_add_u64 v[4:5], v[4:5], 0, s[14:15]
	global_load_dword v107, v[2:3], off offset:256
	global_load_dword v140, v[4:5], off
	v_lshl_add_u64 v[4:5], v[4:5], 0, s[14:15]
	global_load_dword v108, v[2:3], off offset:512
	global_load_dword v141, v[4:5], off
	v_lshl_add_u64 v[4:5], v[4:5], 0, s[14:15]
	global_load_dword v109, v[2:3], off offset:768
	global_load_dword v142, v[4:5], off
	v_lshl_add_u64 v[4:5], v[4:5], 0, s[14:15]
	global_load_dword v110, v[2:3], off offset:1024
	global_load_dword v143, v[4:5], off
	v_lshl_add_u64 v[4:5], v[4:5], 0, s[14:15]
	global_load_dword v111, v[2:3], off offset:1280
	global_load_dword v144, v[4:5], off
	v_lshl_add_u64 v[4:5], v[4:5], 0, s[14:15]
	global_load_dword v112, v[2:3], off offset:1536
	global_load_dword v145, v[4:5], off
	v_lshl_add_u64 v[4:5], v[4:5], 0, s[14:15]
	global_load_dword v113, v[2:3], off offset:1792
	global_load_dword v146, v[4:5], off
	v_lshl_add_u64 v[4:5], v[4:5], 0, s[14:15]
	global_load_dword v114, v[2:3], off offset:2048
	global_load_dword v147, v[4:5], off
	v_lshl_add_u64 v[4:5], v[4:5], 0, s[14:15]
	global_load_dword v115, v[2:3], off offset:2304
	global_load_dword v148, v[4:5], off
	v_lshl_add_u64 v[4:5], v[4:5], 0, s[14:15]
	global_load_dword v116, v[2:3], off offset:2560
	global_load_dword v149, v[4:5], off
	v_lshl_add_u64 v[4:5], v[4:5], 0, s[14:15]
	global_load_dword v117, v[2:3], off offset:2816
	global_load_dword v150, v[4:5], off
	v_lshl_add_u64 v[4:5], v[4:5], 0, s[14:15]
	global_load_dword v118, v[2:3], off offset:3072
	global_load_dword v151, v[4:5], off
	v_lshl_add_u64 v[4:5], v[4:5], 0, s[14:15]
	global_load_dword v119, v[2:3], off offset:3328
	global_load_dword v152, v[4:5], off
	v_lshl_add_u64 v[4:5], v[4:5], 0, s[14:15]
	global_load_dword v120, v[2:3], off offset:3584
	global_load_dword v153, v[4:5], off
	v_lshl_add_u64 v[4:5], v[4:5], 0, s[14:15]
	global_load_dword v138, v[2:3], off offset:3840
	global_load_dword v154, v[4:5], off
	v_lshl_add_u64 v[4:5], v[4:5], 0, s[14:15]
	v_add_co_u32_e32 v2, vcc, 0x1000, v2
	v_addc_co_u32_e32 v3, vcc, 0, v3, vcc
	s_waitcnt vmcnt(0)
	v_fmac_f32_e32 v0, v106, v139
	v_fmac_f32_e32 v0, v107, v140
	v_fmac_f32_e32 v0, v108, v141
	v_fmac_f32_e32 v0, v109, v142
	v_fmac_f32_e32 v0, v110, v143
	v_fmac_f32_e32 v0, v111, v144
	v_fmac_f32_e32 v0, v112, v145
	v_fmac_f32_e32 v0, v113, v146
	v_fmac_f32_e32 v0, v114, v147
	v_fmac_f32_e32 v0, v115, v148
	v_fmac_f32_e32 v0, v116, v149
	v_fmac_f32_e32 v0, v117, v150
	v_fmac_f32_e32 v0, v118, v151
	v_fmac_f32_e32 v0, v119, v152
	v_fmac_f32_e32 v0, v120, v153
	v_fmac_f32_e32 v0, v138, v154
	global_load_dword v106, v[2:3], off
	global_load_dword v139, v[4:5], off
	v_lshl_add_u64 v[4:5], v[4:5], 0, s[14:15]
	global_load_dword v107, v[2:3], off offset:256
	global_load_dword v140, v[4:5], off
	v_lshl_add_u64 v[4:5], v[4:5], 0, s[14:15]
	global_load_dword v108, v[2:3], off offset:512
	global_load_dword v141, v[4:5], off
	v_lshl_add_u64 v[4:5], v[4:5], 0, s[14:15]
	global_load_dword v109, v[2:3], off offset:768
	global_load_dword v142, v[4:5], off
	v_lshl_add_u64 v[4:5], v[4:5], 0, s[14:15]
	global_load_dword v110, v[2:3], off offset:1024
	global_load_dword v143, v[4:5], off
	v_lshl_add_u64 v[4:5], v[4:5], 0, s[14:15]
	global_load_dword v111, v[2:3], off offset:1280
	global_load_dword v144, v[4:5], off
	v_lshl_add_u64 v[4:5], v[4:5], 0, s[14:15]
	global_load_dword v112, v[2:3], off offset:1536
	global_load_dword v145, v[4:5], off
	v_lshl_add_u64 v[4:5], v[4:5], 0, s[14:15]
	global_load_dword v113, v[2:3], off offset:1792
	global_load_dword v146, v[4:5], off
	v_lshl_add_u64 v[4:5], v[4:5], 0, s[14:15]
	global_load_dword v114, v[2:3], off offset:2048
	global_load_dword v147, v[4:5], off
	v_lshl_add_u64 v[4:5], v[4:5], 0, s[14:15]
	global_load_dword v115, v[2:3], off offset:2304
	global_load_dword v148, v[4:5], off
	v_lshl_add_u64 v[4:5], v[4:5], 0, s[14:15]
	global_load_dword v116, v[2:3], off offset:2560
	global_load_dword v149, v[4:5], off
	v_lshl_add_u64 v[4:5], v[4:5], 0, s[14:15]
	global_load_dword v117, v[2:3], off offset:2816
	global_load_dword v150, v[4:5], off
	v_lshl_add_u64 v[4:5], v[4:5], 0, s[14:15]
	global_load_dword v118, v[2:3], off offset:3072
	global_load_dword v151, v[4:5], off
	v_lshl_add_u64 v[4:5], v[4:5], 0, s[14:15]
	global_load_dword v119, v[2:3], off offset:3328
	global_load_dword v152, v[4:5], off
	v_lshl_add_u64 v[4:5], v[4:5], 0, s[14:15]
	global_load_dword v120, v[2:3], off offset:3584
	global_load_dword v153, v[4:5], off
	v_lshl_add_u64 v[4:5], v[4:5], 0, s[14:15]
	global_load_dword v138, v[2:3], off offset:3840
	global_load_dword v154, v[4:5], off
	v_lshl_add_u64 v[4:5], v[4:5], 0, s[14:15]
	v_add_co_u32_e32 v2, vcc, 0x1000, v2
	v_addc_co_u32_e32 v3, vcc, 0, v3, vcc
	s_waitcnt vmcnt(0)
	v_fmac_f32_e32 v0, v106, v139
	v_fmac_f32_e32 v0, v107, v140
	v_fmac_f32_e32 v0, v108, v141
	v_fmac_f32_e32 v0, v109, v142
	v_fmac_f32_e32 v0, v110, v143
	v_fmac_f32_e32 v0, v111, v144
	v_fmac_f32_e32 v0, v112, v145
	v_fmac_f32_e32 v0, v113, v146
	v_fmac_f32_e32 v0, v114, v147
	v_fmac_f32_e32 v0, v115, v148
	v_fmac_f32_e32 v0, v116, v149
	v_fmac_f32_e32 v0, v117, v150
	v_fmac_f32_e32 v0, v118, v151
	v_fmac_f32_e32 v0, v119, v152
	v_fmac_f32_e32 v0, v120, v153
	v_fmac_f32_e32 v0, v138, v154
	s_or_b64 exec, exec, s[10:11]
	v_and_b32_e32 v2, 64, v195
	v_add_u32_e32 v2, 64, v2
	v_xor_b32_e32 v3, 1, v195
	v_cmp_lt_i32_e32 vcc, v3, v2
	s_nop 1
	v_cndmask_b32_e32 v3, v195, v3, vcc
	v_lshlrev_b32_e32 v3, 2, v3
	ds_bpermute_b32 v3, v3, v0
	s_waitcnt lgkmcnt(0)
	v_add_f32_e32 v0, v0, v3
	v_xor_b32_e32 v3, 2, v195
	v_cmp_lt_i32_e32 vcc, v3, v2
	s_nop 1
	v_cndmask_b32_e32 v3, v195, v3, vcc
	v_lshlrev_b32_e32 v3, 2, v3
	ds_bpermute_b32 v3, v3, v0
	s_waitcnt lgkmcnt(0)
	v_add_f32_e32 v0, v0, v3
	v_xor_b32_e32 v3, 4, v195
	v_cmp_lt_i32_e32 vcc, v3, v2
	s_nop 1
	v_cndmask_b32_e32 v3, v195, v3, vcc
	v_lshlrev_b32_e32 v3, 2, v3
	ds_bpermute_b32 v3, v3, v0
	s_waitcnt lgkmcnt(0)
	v_add_f32_e32 v0, v0, v3
	v_xor_b32_e32 v3, 8, v195
	v_cmp_lt_i32_e32 vcc, v3, v2
	s_nop 1
	v_cndmask_b32_e32 v3, v195, v3, vcc
	v_lshlrev_b32_e32 v3, 2, v3
	ds_bpermute_b32 v3, v3, v0
	s_waitcnt lgkmcnt(0)
	v_add_f32_e32 v0, v0, v3
	v_xor_b32_e32 v3, 16, v195
	v_cmp_lt_i32_e32 vcc, v3, v2
	s_nop 1
	v_cndmask_b32_e32 v3, v195, v3, vcc
	v_lshlrev_b32_e32 v3, 2, v3
	ds_bpermute_b32 v3, v3, v0
	s_waitcnt lgkmcnt(0)
	v_add_f32_e32 v0, v0, v3
	v_xor_b32_e32 v3, 32, v195
	v_cmp_lt_i32_e32 vcc, v3, v2
	s_nop 1
	v_cndmask_b32_e32 v2, v195, v3, vcc
	v_lshlrev_b32_e32 v2, 2, v2
	ds_bpermute_b32 v2, v2, v0
	v_cmp_eq_u32_e32 vcc, 0, v210
	s_and_saveexec_b64 s[10:11], vcc
	s_cbranch_execz .LBB0_944
	s_ashr_i32 s9, s8, 31
	s_lshl_b64 s[12:13], s[8:9], 2
	s_add_u32 s12, s4, s12
	s_waitcnt lgkmcnt(0)
	v_add_f32_e32 v0, v0, v2
	s_addc_u32 s13, s5, s13
	global_store_dword v193, v0, s[12:13]

.LBB0_945:
	s_add_i32 s8, s8, 0x200
	s_and_b32 s8, s8, 0x3ff
	s_cmp_eq_u32 s16, 3
	s_cselect_b32 s0, 0x580, 0
	s_add_i32 s8, s8, s0
	s_cmpk_gt_i32 s8, 0x83f
	s_cbranch_scc1 .LBB0_984
	s_add_i32 s0, s16, 1
	v_lshlrev_b32_e32 v0, 2, v210
	s_mul_i32 s9, s16, 0x580000
	s_waitcnt lgkmcnt(0)
	v_and_b32_e32 v2, 60, v0
	v_lshlrev_b32_e32 v0, 3, v210
	s_add_u32 s10, s4, s9
	v_and_b32_e32 v0, 56, v0
	s_mul_i32 s7, s0, 0xb00000
	s_addc_u32 s11, s5, 0
	v_mul_u32_u24_e32 v5, 0x104, v0
	v_lshlrev_b32_e32 v0, 1, v0
	v_lshrrev_b32_e32 v76, 3, v210
	v_lshl_add_u64 v[6:7], s[10:11], 0, v[0:1]
	s_mov_b64 s[10:11], 0x2d00000
	s_add_u32 s2, s2, s7
	v_lshrrev_b32_e32 v66, 4, v210
	v_lshlrev_b32_e32 v4, 2, v2
	v_lshl_add_u64 v[68:69], v[6:7], 0, s[10:11]
	v_lshlrev_b32_e32 v6, 2, v76
	s_addc_u32 s3, s3, 0
	s_lshl_b32 s0, s0, 10
	v_add_u32_e32 v3, s6, v4
	v_add3_u32 v77, s6, v5, v6
	v_or_b32_e32 v5, 4, v66
	s_movk_i32 s6, 0x104
	v_lshl_add_u64 v[70:71], s[2:3], 0, v[0:1]
	s_mul_i32 s9, s16, 0xb00000
	s_add_u32 s2, s78, s9
	v_mul_u32_u24_e32 v6, 0x104, v5
	v_mad_u32_u24 v7, v5, s6, v205
	v_mad_u32_u24 v9, v5, s6, v206
	v_mad_u32_u24 v10, v5, s6, v207
	s_addc_u32 s3, s79, 0
	v_mov_b32_e32 v5, v1
	v_lshl_add_u64 v[72:73], s[2:3], 0, v[4:5]
	s_lshl_b64 s[2:3], s[0:1], 2
	v_mul_u32_u24_e32 v8, 0x104, v66
	s_add_u32 s2, s72, s2
	v_or_b32_e32 v78, 8, v76
	v_or_b32_e32 v79, 16, v76
	v_or_b32_e32 v80, 24, v76
	v_or_b32_e32 v81, 32, v76
	v_or_b32_e32 v82, 40, v76
	v_or_b32_e32 v83, 48, v76
	v_or_b32_e32 v84, 56, v76
	s_addc_u32 s3, s73, s3
	v_mov_b32_e32 v67, v1
	s_lshl_b32 s6, s8, 2
	s_lshl_b32 s9, s8, 6
	v_lshlrev_b32_e32 v0, 2, v2
	v_add_u32_e32 v85, v3, v6
	v_add_u32_e32 v86, v3, v9
	v_add_u32_e32 v87, v3, v8
	v_add_u32_e32 v88, v3, v7
	v_add_u32_e32 v89, v3, v10
	s_branch .LBB0_950
